# top-16 block selection and slot ordering rewritten with DPP row reductions (no ds_bpermute chains)
# speedup vs baseline: 1.0842x; 1.0078x over previous
; #define LAS __attribute__((address_space(3)))
; __device__ __forceinline__ void nsa_wave(CArgs* Ap, int l, int b, int g, int tq0, const LAS float* lut, LAS float* imp, int lane) {
;     ...
;     const int cur = tq0 >> 6;
;     int selreg = -1;
;     if (cur < 16) selreg = (n16 <= cur) ? n16 : -1;
;     else {
;         const int sq = lane >> 4, tsel = tq0 + sq; (void)tsel;
;         float sc[8];
; #pragma unroll
;         for (int jj = 0; jj < 8; ++jj) { const int j = n16 + 16 * jj;
;             float v;
;             if (j > cur) v = -1.f;
;             else if (j == 0 || j == cur || j == cur - 1) v = 1e4f;
;             else { const LAS float* ip = imp + sq * 512 + 4 * j; v = ip[0] + 2.f * (ip[-1] + ip[-2] + ip[-3]) + ip[-4]; }
;             sc[jj] = v; }
.LBB0_943:
	s_waitcnt lgkmcnt(0)
	s_ashr_i32 s21, s19, 6
	s_cmp_gt_i32 s21, 15
	s_cbranch_scc1 .Ltk_full
	v_cmp_ge_i32_e32 vcc, s21, v128
	s_nop 1
	v_cndmask_b32_e32 v210, -1, v128, vcc
	s_branch .LBB0_1237
.Ltk_full:
	s_add_i32 s22, s21, -1
	ds_read_b128 v[24:27], v134
	ds_read_b32 v56, v133
	ds_read_b128 v[28:31], v137
	ds_read_b32 v57, v136
	ds_read_b128 v[32:35], v140
	ds_read_b32 v58, v139
	ds_read_b128 v[36:39], v143
	ds_read_b32 v59, v142
	ds_read_b128 v[40:43], v154
	ds_read_b32 v60, v153
	ds_read_b128 v[44:47], v157
	ds_read_b32 v61, v156
	ds_read_b128 v[48:51], v160
	ds_read_b32 v62, v159
	ds_read_b128 v[52:55], v163
	ds_read_b32 v63, v162
	v_mov_b32_e32 v64, 0x461c4000
	v_cmp_eq_u32_e64 s[46:47], s21, v128
	v_cmp_eq_u32_e64 s[48:49], s22, v128
	s_or_b64 s[50:51], s[46:47], s[48:49]
	s_or_b64 s[50:51], s[50:51], s[4:5]
	v_cmp_eq_u32_e64 s[46:47], s21, v135
	v_cmp_eq_u32_e64 s[48:49], s22, v135
	s_or_b64 s[52:53], s[46:47], s[48:49]
	v_cmp_eq_u32_e64 s[46:47], s21, v138
	v_cmp_eq_u32_e64 s[48:49], s22, v138
	s_or_b64 s[54:55], s[46:47], s[48:49]
	v_cmp_eq_u32_e64 s[46:47], s21, v141
	v_cmp_eq_u32_e64 s[48:49], s22, v141
	s_or_b64 s[56:57], s[46:47], s[48:49]
	v_cmp_eq_u32_e64 s[46:47], s21, v152
	v_cmp_eq_u32_e64 s[48:49], s22, v152
	s_or_b64 s[58:59], s[46:47], s[48:49]
	v_cmp_eq_u32_e64 s[46:47], s21, v155
	v_cmp_eq_u32_e64 s[48:49], s22, v155
	s_or_b64 s[60:61], s[46:47], s[48:49]
	v_cmp_eq_u32_e64 s[46:47], s21, v158
	v_cmp_eq_u32_e64 s[48:49], s22, v158
	s_or_b64 s[62:63], s[46:47], s[48:49]
	v_cmp_eq_u32_e64 s[46:47], s21, v161
	v_cmp_eq_u32_e64 s[48:49], s22, v161
	s_or_b64 s[64:65], s[46:47], s[48:49]
	s_waitcnt lgkmcnt(14)
	v_add_f32_e32 v26, v27, v26
	v_add_f32_e32 v25, v26, v25
	v_fmac_f32_e32 v56, 2.0, v25
	v_add_f32_e32 v228, v24, v56
	s_waitcnt lgkmcnt(12)
	v_add_f32_e32 v30, v31, v30
	v_add_f32_e32 v29, v30, v29
	v_fmac_f32_e32 v57, 2.0, v29
	v_add_f32_e32 v229, v28, v57
	s_waitcnt lgkmcnt(10)
	v_add_f32_e32 v34, v35, v34
	v_add_f32_e32 v33, v34, v33
	v_fmac_f32_e32 v58, 2.0, v33
	v_add_f32_e32 v230, v32, v58
	s_waitcnt lgkmcnt(8)
	v_add_f32_e32 v38, v39, v38
	v_add_f32_e32 v37, v38, v37
	v_fmac_f32_e32 v59, 2.0, v37
	v_add_f32_e32 v231, v36, v59
	s_waitcnt lgkmcnt(6)
	v_add_f32_e32 v42, v43, v42
	v_add_f32_e32 v41, v42, v41
	v_fmac_f32_e32 v60, 2.0, v41
	v_add_f32_e32 v232, v40, v60
	s_waitcnt lgkmcnt(4)
	v_add_f32_e32 v46, v47, v46
	v_add_f32_e32 v45, v46, v45
	v_fmac_f32_e32 v61, 2.0, v45
	v_add_f32_e32 v233, v44, v61
	s_waitcnt lgkmcnt(2)
	v_add_f32_e32 v50, v51, v50
	v_add_f32_e32 v49, v50, v49
	v_fmac_f32_e32 v62, 2.0, v49
	v_add_f32_e32 v234, v48, v62
	s_waitcnt lgkmcnt(0)
	v_add_f32_e32 v54, v55, v54
	v_add_f32_e32 v53, v54, v53
	v_fmac_f32_e32 v63, 2.0, v53
	v_add_f32_e32 v235, v52, v63
	v_cndmask_b32_e64 v228, v228, v64, s[50:51]
	v_cndmask_b32_e64 v229, v229, v64, s[52:53]
	v_cndmask_b32_e64 v230, v230, v64, s[54:55]
	v_cndmask_b32_e64 v231, v231, v64, s[56:57]
	v_cndmask_b32_e64 v232, v232, v64, s[58:59]
	v_cndmask_b32_e64 v233, v233, v64, s[60:61]
	v_cndmask_b32_e64 v234, v234, v64, s[62:63]
	v_cndmask_b32_e64 v235, v235, v64, s[64:65]
	v_cmp_ge_i32_e64 s[52:53], s21, v135
	v_cmp_ge_i32_e64 s[54:55], s21, v138
	v_cmp_ge_i32_e64 s[56:57], s21, v141
	v_cmp_ge_i32_e64 s[58:59], s21, v152
	v_cmp_ge_i32_e64 s[60:61], s21, v155
	v_cmp_ge_i32_e64 s[62:63], s21, v158
	v_cmp_ge_i32_e64 s[64:65], s21, v161
	v_cndmask_b32_e64 v229, -1.0, v229, s[52:53]
	v_cndmask_b32_e64 v230, -1.0, v230, s[54:55]
	v_cndmask_b32_e64 v231, -1.0, v231, s[56:57]
	v_cndmask_b32_e64 v232, -1.0, v232, s[58:59]
	v_cndmask_b32_e64 v233, -1.0, v233, s[60:61]
	v_cndmask_b32_e64 v234, -1.0, v234, s[62:63]
	v_cndmask_b32_e64 v235, -1.0, v235, s[64:65]
	s_mov_b32 s23, 0
; __device__ __forceinline__ void nsa_wave(CArgs* Ap, int l, int b, int g, int tq0, const LAS float* lut, LAS float* imp, int lane) {
;     ...
;         for (int s = 0; s < 16; ++s) {
;             float bv = sc[0]; int bj = n16;
; #pragma unroll
;             for (int jj = 1; jj < 8; ++jj) if (sc[jj] > bv) { bv = sc[jj]; bj = n16 + 16 * jj; }
; #pragma unroll
;             for (int off = 1; off < 16; off <<= 1) { const float ov = __shfl_xor(bv, off); const int oj = __shfl_xor(bj, off); if (ov > bv || (ov == bv && oj < bj)) { bv = ov; bj = oj; } }
;             if (n16 == s) selreg = (bv >= 0.f) ? bj : -1;
; #pragma unroll
;             for (int jj = 0; jj < 8; ++jj) if (bj == n16 + 16 * jj) sc[jj] = -2.f;
;         }
;     }
;     if (cur >= 16) {
;         const int fj = selreg;
;         const int key = (fj < 0) ? ((1 << 20) + n16) : ((fj == 0 || fj == cur || fj == cur - 1) ? fj : (1 << 10) + fj);
;         int rank = 0;
; #pragma unroll
;         for (int o = 1; o < 16; ++o) { const int other = __shfl(key, (lane & 48) | ((n16 + o) & 15)); rank += (other < key) ? 1 : 0; }
;         selreg = __builtin_amdgcn_ds_permute(((lane & 48) | rank) << 2, fj);
.Ltk_loop:
	v_max3_f32 v238, v228, v229, v230
	v_max3_f32 v239, v231, v232, v233
	v_max3_f32 v238, v234, v235, v238
	v_max_f32_e32 v236, v238, v239
	s_nop 1
	v_max_f32_dpp v236, v236, v236 quad_perm:[1,0,3,2] row_mask:0xf bank_mask:0xf
	s_nop 1
	v_max_f32_dpp v236, v236, v236 quad_perm:[2,3,0,1] row_mask:0xf bank_mask:0xf
	s_nop 1
	v_max_f32_dpp v236, v236, v236 row_half_mirror row_mask:0xf bank_mask:0xf
	s_nop 1
	v_max_f32_dpp v236, v236, v236 row_mirror row_mask:0xf bank_mask:0xf
	v_cmp_eq_f32_e64 s[50:51], v228, v236
	v_cmp_eq_f32_e64 s[52:53], v229, v236
	v_cmp_eq_f32_e64 s[54:55], v230, v236
	v_cmp_eq_f32_e64 s[56:57], v231, v236
	v_cmp_eq_f32_e64 s[58:59], v232, v236
	v_cmp_eq_f32_e64 s[60:61], v233, v236
	v_cmp_eq_f32_e64 s[62:63], v234, v236
	v_cmp_eq_f32_e64 s[64:65], v235, v236
	v_bfrev_b32_e32 v239, -2
	v_cndmask_b32_e64 v244, v239, v128, s[50:51]
	v_cndmask_b32_e64 v245, v239, v135, s[52:53]
	v_cndmask_b32_e64 v246, v239, v138, s[54:55]
	v_cndmask_b32_e64 v247, v239, v141, s[56:57]
	v_cndmask_b32_e64 v248, v239, v152, s[58:59]
	v_cndmask_b32_e64 v249, v239, v155, s[60:61]
	v_cndmask_b32_e64 v250, v239, v158, s[62:63]
	v_cndmask_b32_e64 v251, v239, v161, s[64:65]
	v_min3_u32 v238, v244, v245, v246
	v_min3_u32 v239, v247, v248, v249
	v_min3_u32 v238, v250, v251, v238
	v_min_u32_e32 v237, v238, v239
	s_nop 1
	v_min_u32_dpp v237, v237, v237 quad_perm:[1,0,3,2] row_mask:0xf bank_mask:0xf
	s_nop 1
	v_min_u32_dpp v237, v237, v237 quad_perm:[2,3,0,1] row_mask:0xf bank_mask:0xf
	s_nop 1
	v_min_u32_dpp v237, v237, v237 row_half_mirror row_mask:0xf bank_mask:0xf
	s_nop 1
	v_min_u32_dpp v237, v237, v237 row_mirror row_mask:0xf bank_mask:0xf
	v_cmp_le_f32_e64 s[46:47], 0, v236
	v_cmp_eq_u32_e64 s[48:49], s23, v128
	v_cmp_eq_u32_e64 s[50:51], v128, v237
	v_cmp_eq_u32_e64 s[52:53], v135, v237
	v_cmp_eq_u32_e64 s[54:55], v138, v237
	v_cmp_eq_u32_e64 s[56:57], v141, v237
	v_cmp_eq_u32_e64 s[58:59], v152, v237
	v_cmp_eq_u32_e64 s[60:61], v155, v237
	v_cmp_eq_u32_e64 s[62:63], v158, v237
	v_cmp_eq_u32_e64 s[64:65], v161, v237
	v_cndmask_b32_e64 v238, -1, v237, s[46:47]
	v_mov_b32_e32 v239, -2.0
	s_add_i32 s23, s23, 1
	v_cndmask_b32_e64 v210, v210, v238, s[48:49]
	v_cndmask_b32_e64 v228, v228, v239, s[50:51]
	v_cndmask_b32_e64 v229, v229, v239, s[52:53]
	v_cndmask_b32_e64 v230, v230, v239, s[54:55]
	v_cndmask_b32_e64 v231, v231, v239, s[56:57]
	v_cndmask_b32_e64 v232, v232, v239, s[58:59]
	v_cndmask_b32_e64 v233, v233, v239, s[60:61]
	v_cndmask_b32_e64 v234, v234, v239, s[62:63]
	v_cndmask_b32_e64 v235, v235, v239, s[64:65]
	s_cmp_lt_u32 s23, 16
	s_cbranch_scc1 .Ltk_loop
	v_cmp_eq_u32_e64 s[46:47], 0, v210
	v_cmp_eq_u32_e64 s[48:49], s21, v210
	v_cmp_eq_u32_e64 s[50:51], s22, v210
	v_cmp_lt_i32_e64 s[52:53], -1, v210
	v_add_u32_e32 v240, 0x400, v210
	s_or_b64 s[46:47], s[46:47], s[48:49]
	s_or_b64 s[46:47], s[46:47], s[50:51]
	v_cndmask_b32_e64 v240, v240, v210, s[46:47]
	v_cndmask_b32_e64 v240, v164, v240, s[52:53]
	s_nop 1
	v_sub_u32_dpp v25, v240, v240 row_ror:1 row_mask:0xf bank_mask:0xf
	v_sub_u32_dpp v26, v240, v240 row_ror:2 row_mask:0xf bank_mask:0xf
	v_sub_u32_dpp v27, v240, v240 row_ror:3 row_mask:0xf bank_mask:0xf
	v_sub_u32_dpp v28, v240, v240 row_ror:4 row_mask:0xf bank_mask:0xf
	v_sub_u32_dpp v29, v240, v240 row_ror:5 row_mask:0xf bank_mask:0xf
	v_sub_u32_dpp v30, v240, v240 row_ror:6 row_mask:0xf bank_mask:0xf
	v_sub_u32_dpp v31, v240, v240 row_ror:7 row_mask:0xf bank_mask:0xf
	v_sub_u32_dpp v32, v240, v240 row_ror:8 row_mask:0xf bank_mask:0xf
	v_sub_u32_dpp v33, v240, v240 row_ror:9 row_mask:0xf bank_mask:0xf
	v_sub_u32_dpp v34, v240, v240 row_ror:10 row_mask:0xf bank_mask:0xf
	v_sub_u32_dpp v35, v240, v240 row_ror:11 row_mask:0xf bank_mask:0xf
	v_sub_u32_dpp v36, v240, v240 row_ror:12 row_mask:0xf bank_mask:0xf
	v_sub_u32_dpp v37, v240, v240 row_ror:13 row_mask:0xf bank_mask:0xf
	v_sub_u32_dpp v38, v240, v240 row_ror:14 row_mask:0xf bank_mask:0xf
	v_sub_u32_dpp v39, v240, v240 row_ror:15 row_mask:0xf bank_mask:0xf
	v_lshrrev_b32_e32 v25, 31, v25
	v_lshrrev_b32_e32 v26, 31, v26
	v_lshrrev_b32_e32 v27, 31, v27
	v_lshrrev_b32_e32 v28, 31, v28
	v_lshrrev_b32_e32 v29, 31, v29
	v_lshrrev_b32_e32 v30, 31, v30
	v_lshrrev_b32_e32 v31, 31, v31
	v_lshrrev_b32_e32 v32, 31, v32
	v_lshrrev_b32_e32 v33, 31, v33
	v_lshrrev_b32_e32 v34, 31, v34
	v_lshrrev_b32_e32 v35, 31, v35
	v_lshrrev_b32_e32 v36, 31, v36
	v_lshrrev_b32_e32 v37, 31, v37
	v_lshrrev_b32_e32 v38, 31, v38
	v_lshrrev_b32_e32 v39, 31, v39
	v_add3_u32 v241, v25, v26, v27
	v_add3_u32 v241, v241, v28, v29
	v_add3_u32 v241, v241, v30, v31
	v_add3_u32 v241, v241, v32, v33
	v_add3_u32 v241, v241, v34, v35
	v_add3_u32 v241, v241, v36, v37
	v_add3_u32 v241, v241, v38, v39
	v_or_b32_e32 v241, v241, v129
	v_lshlrev_b32_e32 v241, 2, v241
	ds_permute_b32 v210, v241, v210
